# grid barriers after phases 4 and 5 replaced by per-group (8 workgroups, same XCD) arrival counters
# baseline (speedup 1.0000x reference)
; __device__ __forceinline__ void grid_barrier(unsigned* ctr, const unsigned k) {
;   __syncthreads();
;   if (threadIdx.x == 0) {
;     __hip_atomic_fetch_add(ctr, 1u, __ATOMIC_RELEASE, __HIP_MEMORY_SCOPE_AGENT);
;     const unsigned target = k * gridDim.x;
;     while (__hip_atomic_load(ctr, __ATOMIC_RELAXED, __HIP_MEMORY_SCOPE_AGENT) < target) __builtin_amdgcn_s_sleep(1);
;     __builtin_amdgcn_fence(__ATOMIC_ACQUIRE, "agent");
;   }
;   __syncthreads();
.LBB0_387:
	v_readlane_b32 s42, v247, 0
	v_readlane_b32 s43, v247, 1
	s_waitcnt vmcnt(0)
	s_barrier
	s_and_saveexec_b64 s[4:5], s[42:43]
	s_cbranch_execz .LBB0_393
	s_waitcnt vmcnt(0)
	s_and_b32 vcc_lo, s89, 7
	s_lshl_b32 vcc_lo, vcc_lo, 3
	s_bfe_u32 vcc_hi, s89, 0x30003
	s_or_b32 vcc_lo, vcc_lo, vcc_hi
	s_lshl_b32 vcc_lo, vcc_lo, 2
	v_mov_b32_e32 v0, vcc_lo
	v_mov_b32_e32 v1, 1
	global_atomic_add v0, v1, s[44:45] offset:1792
	s_mov_b32 m0, 0
.Lgg4_poll:
	global_load_dword v1, v0, s[44:45] offset:1792 sc1
	s_waitcnt vmcnt(0)
	v_cmp_le_u32_e32 vcc, 8, v1
	s_cbranch_vccnz .Lgg4_done
	s_sleep 1
	s_add_u32 m0, m0, 1
	s_cmp_lt_u32 m0, 0x40000
	s_cbranch_scc1 .Lgg4_poll

; __device__ __forceinline__ void grid_barrier(unsigned* ctr, const unsigned k) {
;   __syncthreads();
;   if (threadIdx.x == 0) {
;     __hip_atomic_fetch_add(ctr, 1u, __ATOMIC_RELEASE, __HIP_MEMORY_SCOPE_AGENT);
;     const unsigned target = k * gridDim.x;
;     while (__hip_atomic_load(ctr, __ATOMIC_RELAXED, __HIP_MEMORY_SCOPE_AGENT) < target) __builtin_amdgcn_s_sleep(1);
;     __builtin_amdgcn_fence(__ATOMIC_ACQUIRE, "agent");
;   }
;   __syncthreads();
.LBB0_418:
	s_waitcnt vmcnt(0)
	s_barrier
	s_and_saveexec_b64 s[6:7], s[42:43]
	s_cbranch_execz .LBB0_424
	s_waitcnt vmcnt(0)
	s_and_b32 vcc_lo, s89, 7
	s_lshl_b32 vcc_lo, vcc_lo, 3
	s_bfe_u32 vcc_hi, s89, 0x30003
	s_or_b32 vcc_lo, vcc_lo, vcc_hi
	s_lshl_b32 vcc_lo, vcc_lo, 2
	v_mov_b32_e32 v0, vcc_lo
	v_mov_b32_e32 v1, 1
	global_atomic_add v0, v1, s[44:45] offset:1792
	s_mov_b32 m0, 0
.Lgg5_poll:
	global_load_dword v1, v0, s[44:45] offset:1792 sc1
	s_waitcnt vmcnt(0)
	v_cmp_le_u32_e32 vcc, 16, v1
	s_cbranch_vccnz .Lgg5_done
	s_sleep 1
	s_add_u32 m0, m0, 1
	s_cmp_lt_u32 m0, 0x40000
	s_cbranch_scc1 .Lgg5_poll

; __device__ __forceinline__ void phase6(const Params& p, unsigned char* smem) {
;   const u16* MERGED = (const u16*)(p.ws + OFF_EXTRA);
;   const u16* wot = (const u16*)(p.ws + OFF_W3) + 2 * 1024 * 1024;
;   float* PSUM = (float*)(p.ws + OFF_PSUM);
;   const int xcd = blockIdx.x & 7, lw = blockIdx.x >> 3, LW = (gridDim.x - xcd + 7) >> 3;
;   for (int i = lw;; i += LW) {
;     int mt, nt; if (!tile_map(i, xcd, 128, 8, mt, nt)) break;
;     const int m0 = mt * 128, n0 = nt * 128;
;     f32x16 acc[2][2]; zero_acc(acc);
;     gemm_kloop(acc, [&](int m) { return MERGED + (size_t)m * 1024; }, [](int k0) { return (size_t)k0; }, wot, m0, n0, smem);
.LBB0_424:
	s_or_b64 exec, exec, s[6:7]
	s_andn2_b64 vcc, exec, s[4:5]
	s_barrier
	s_cbranch_vccnz .LBB0_441
	s_add_u32 s4, s36, 0xc5d9000
	s_addc_u32 s5, s37, 0
	s_add_u32 s6, s36, 0xec1d000
	s_addc_u32 s7, s37, 0
	s_add_u32 s2, s36, 0xf123000
	s_addc_u32 s26, s37, 0
	s_lshr_b32 s8, s89, 6
	s_and_b32 s22, s8, 8
	s_load_dwordx2 s[8:9], s[0:1], 0x0
	s_load_dwordx2 s[10:11], s[0:1], 0x88
	s_load_dwordx2 s[54:55], s[0:1], 0x80
	s_mov_b64 s[56:57], 0x10000
	s_mov_b32 s61, 16
	s_lshl_b32 s27, s73, 7
	s_add_u32 s12, s36, 0xc5d9080
	s_addc_u32 s13, s37, 0
	v_mov_b32_e32 v97, 0
	s_mov_b64 s[14:15], 0x10000
	s_mov_b64 s[16:17], 0x20000
	s_mov_b64 s[18:19], 0x30000
	s_mov_b32 s28, 0x10000
	s_mov_b32 s29, 0x20000
	s_mov_b32 s30, 0x30000
	s_movk_i32 s31, 0x90
	s_mov_b32 s34, 0xfffffc0
	s_movk_i32 s35, 0x210
	s_branch .LBB0_428
